# preheader vmcnt(0) flush dropped before three GEMM K-loops; MLA row-max chain split into two interleaved chains
# baseline (speedup 1.0000x reference)
; template <class Epi, bool SEG>
; __device__ __forceinline__ void gemm_phase(LAS unsigned char* lds, const Gemm g, const int G, const int cidx, const Epi& E) {
;     ...
;         const bool has_next = S.next(ui + 1, nxt);
;         const char* nA = has_next ? (const char*)g.A + (long)nxt.pm * (long)tstepA + aoff0 : cA; const char* nB = has_next ? (const char*)g.Bt + (size_t)nxt.pn * tstepB : cB;
;     ...
;         for (int a = 0; a < 2; ++a)
; #pragma unroll
;             for (int b = 0; b < 2; ++b)
; #pragma unroll
;                 for (int m = 0; m < 4; ++m)
; #pragma unroll
;                     for (int n = 0; n < 2; ++n) acc[a][b][m][n] = (f32x4){0.f, 0.f, 0.f, 0.f};
.LBB0_705:
	s_ashr_i32 s19, s18, 31
	s_lshl_b64 s[20:21], s[18:19], 19
	s_add_u32 s20, s6, s20
	s_addc_u32 s21, s7, s21
	s_and_b64 s[22:23], s[46:47], exec
	s_cselect_b32 s19, s21, s41
	s_cselect_b32 s54, s20, s40
	s_ashr_i32 s17, s16, 31
	s_lshl_b64 s[22:23], s[16:17], 19
	s_add_u32 s22, s8, s22
	s_addc_u32 s23, s1, s23
	s_and_b64 s[50:51], s[46:47], exec
	s_cselect_b32 s17, s23, s49
	s_cselect_b32 s55, s22, s48
	s_add_u32 s40, s40, 0x40080
	s_addc_u32 s41, s41, 0
	s_add_u32 s56, s48, 0x100
	v_mov_b32_e32 v2, 0
	s_addc_u32 s57, s49, 0
	s_mov_b32 s58, -2
	s_waitcnt lgkmcnt(0)
	v_mov_b32_e32 v3, v2
	v_mov_b32_e32 v4, v2
	v_mov_b32_e32 v5, v2
	v_mov_b32_e32 v6, v2
	v_mov_b32_e32 v7, v2
	v_mov_b32_e32 v8, v2
	v_mov_b32_e32 v9, v2
	v_mov_b32_e32 v22, v2
	v_mov_b32_e32 v23, v2
	v_mov_b32_e32 v24, v2
	v_mov_b32_e32 v25, v2
	v_mov_b32_e32 v26, v2
	v_mov_b32_e32 v27, v2
	v_mov_b32_e32 v28, v2
	v_mov_b32_e32 v29, v2
	v_mov_b32_e32 v38, v2
	v_mov_b32_e32 v39, v2
	v_mov_b32_e32 v40, v2
	v_mov_b32_e32 v41, v2
	v_mov_b32_e32 v42, v2
	v_mov_b32_e32 v43, v2
	v_mov_b32_e32 v44, v2
	v_mov_b32_e32 v45, v2
	v_mov_b32_e32 v54, v2
	v_mov_b32_e32 v55, v2
	v_mov_b32_e32 v56, v2
	v_mov_b32_e32 v57, v2
	v_mov_b32_e32 v58, v2
	v_mov_b32_e32 v59, v2
	v_mov_b32_e32 v60, v2
	v_mov_b32_e32 v61, v2
	v_mov_b32_e32 v10, v2
	v_mov_b32_e32 v11, v2
	v_mov_b32_e32 v12, v2
	v_mov_b32_e32 v13, v2
	v_mov_b32_e32 v18, v2
	v_mov_b32_e32 v19, v2
	v_mov_b32_e32 v20, v2
	v_mov_b32_e32 v21, v2
	v_mov_b32_e32 v30, v2
	v_mov_b32_e32 v31, v2
	v_mov_b32_e32 v32, v2
	v_mov_b32_e32 v33, v2
	v_mov_b32_e32 v34, v2
	v_mov_b32_e32 v35, v2
	v_mov_b32_e32 v36, v2
	v_mov_b32_e32 v37, v2
	v_mov_b32_e32 v46, v2
	v_mov_b32_e32 v47, v2
	v_mov_b32_e32 v48, v2
	v_mov_b32_e32 v49, v2
	v_mov_b32_e32 v50, v2
	v_mov_b32_e32 v51, v2
	v_mov_b32_e32 v52, v2
	v_mov_b32_e32 v53, v2
	v_mov_b32_e32 v62, v2
	v_mov_b32_e32 v63, v2
	v_mov_b32_e32 v64, v2
	v_mov_b32_e32 v65, v2
	v_mov_b32_e32 v66, v2
	v_mov_b32_e32 v67, v2
	v_mov_b32_e32 v68, v2
	v_mov_b32_e32 v69, v2
	v_mov_b32_e32 v70, v2
	v_mov_b32_e32 v71, v2
	v_mov_b32_e32 v72, v2
	v_mov_b32_e32 v73, v2
	v_mov_b32_e32 v74, v2
	v_mov_b32_e32 v75, v2
	v_mov_b32_e32 v76, v2
	v_mov_b32_e32 v77, v2
	v_mov_b32_e32 v86, v2
	v_mov_b32_e32 v87, v2
	v_mov_b32_e32 v88, v2
	v_mov_b32_e32 v89, v2
	v_mov_b32_e32 v90, v2
	v_mov_b32_e32 v91, v2
	v_mov_b32_e32 v92, v2
	v_mov_b32_e32 v93, v2
	v_mov_b32_e32 v102, v2
	v_mov_b32_e32 v103, v2
	v_mov_b32_e32 v104, v2
	v_mov_b32_e32 v105, v2
	v_mov_b32_e32 v106, v2
	v_mov_b32_e32 v107, v2
	v_mov_b32_e32 v108, v2
	v_mov_b32_e32 v109, v2
	v_mov_b32_e32 v118, v2
	v_mov_b32_e32 v119, v2
	v_mov_b32_e32 v120, v2
	v_mov_b32_e32 v121, v2
	v_mov_b32_e32 v122, v2
	v_mov_b32_e32 v123, v2
	v_mov_b32_e32 v124, v2
	v_mov_b32_e32 v125, v2
	v_mov_b32_e32 v78, v2
	v_mov_b32_e32 v79, v2
	v_mov_b32_e32 v80, v2
	v_mov_b32_e32 v81, v2
	v_mov_b32_e32 v82, v2
	v_mov_b32_e32 v83, v2
	v_mov_b32_e32 v84, v2
	v_mov_b32_e32 v85, v2
	v_mov_b32_e32 v94, v2
	v_mov_b32_e32 v95, v2
	v_mov_b32_e32 v96, v2
	v_mov_b32_e32 v97, v2
	v_mov_b32_e32 v98, v2
	v_mov_b32_e32 v99, v2
	v_mov_b32_e32 v100, v2
	v_mov_b32_e32 v101, v2
	v_mov_b32_e32 v110, v2
	v_mov_b32_e32 v111, v2
	v_mov_b32_e32 v112, v2
	v_mov_b32_e32 v113, v2
	v_mov_b32_e32 v114, v2
	v_mov_b32_e32 v115, v2
	v_mov_b32_e32 v116, v2
	v_mov_b32_e32 v117, v2
	v_mov_b32_e32 v126, v2
	v_mov_b32_e32 v127, v2
	v_mov_b32_e32 v128, v2
	v_mov_b32_e32 v129, v2
	v_mov_b32_e32 v134, v2
	v_mov_b32_e32 v135, v2
	v_mov_b32_e32 v136, v2
	v_mov_b32_e32 v137, v2

; template <class Epi, bool SEG>
; __device__ __forceinline__ void gemm_phase(LAS unsigned char* lds, const Gemm g, const int G, const int cidx, const Epi& E) {
;     ...
;         const bool has_next = S.next(ui + 1, nxt);
;         const char* nA = has_next ? (const char*)g.A + (long)nxt.pm * (long)tstepA + aoff0 : cA; const char* nB = has_next ? (const char*)g.Bt + (size_t)nxt.pn * tstepB : cB;
;     ...
;         for (int a = 0; a < 2; ++a)
; #pragma unroll
;             for (int b = 0; b < 2; ++b)
; #pragma unroll
;                 for (int m = 0; m < 4; ++m)
; #pragma unroll
;                     for (int n = 0; n < 2; ++n) acc[a][b][m][n] = (f32x4){0.f, 0.f, 0.f, 0.f};
.LBB0_785:
	s_ashr_i32 s15, s14, 31
	s_lshl_b64 s[18:19], s[14:15], 19
	v_readlane_b32 s15, v255, 15
	s_add_u32 s18, s15, s18
	v_readlane_b32 s15, v255, 16
	s_addc_u32 s19, s15, s19
	s_and_b64 s[6:7], s[6:7], exec
	s_cselect_b32 s15, s19, s23
	s_cselect_b32 s21, s18, s22
	s_add_u32 s6, s40, 0x3e080
	s_addc_u32 s7, s41, 0
	s_add_u32 s52, s22, 0x100
	v_mov_b32_e32 v2, 0
	s_addc_u32 s53, s23, 0
	s_mov_b32 s54, -2
	v_mov_b32_e32 v3, v2
	v_mov_b32_e32 v4, v2
	v_mov_b32_e32 v5, v2
	v_mov_b32_e32 v70, v2
	v_mov_b32_e32 v71, v2
	v_mov_b32_e32 v72, v2
	v_mov_b32_e32 v73, v2
	v_mov_b32_e32 v10, v2
	v_mov_b32_e32 v11, v2
	v_mov_b32_e32 v12, v2
	v_mov_b32_e32 v13, v2
	v_mov_b32_e32 v78, v2
	v_mov_b32_e32 v79, v2
	v_mov_b32_e32 v80, v2
	v_mov_b32_e32 v81, v2
	v_mov_b32_e32 v22, v2
	v_mov_b32_e32 v23, v2
	v_mov_b32_e32 v24, v2
	v_mov_b32_e32 v25, v2
	v_mov_b32_e32 v86, v2
	v_mov_b32_e32 v87, v2
	v_mov_b32_e32 v88, v2
	v_mov_b32_e32 v89, v2
	v_mov_b32_e32 v26, v2
	v_mov_b32_e32 v27, v2
	v_mov_b32_e32 v28, v2
	v_mov_b32_e32 v29, v2
	v_mov_b32_e32 v90, v2
	v_mov_b32_e32 v91, v2
	v_mov_b32_e32 v92, v2
	v_mov_b32_e32 v93, v2
	v_mov_b32_e32 v6, v2
	v_mov_b32_e32 v7, v2
	v_mov_b32_e32 v8, v2
	v_mov_b32_e32 v9, v2
	v_mov_b32_e32 v74, v2
	v_mov_b32_e32 v75, v2
	v_mov_b32_e32 v76, v2
	v_mov_b32_e32 v77, v2
	v_mov_b32_e32 v18, v2
	v_mov_b32_e32 v19, v2
	v_mov_b32_e32 v20, v2
	v_mov_b32_e32 v21, v2
	v_mov_b32_e32 v82, v2
	v_mov_b32_e32 v83, v2
	v_mov_b32_e32 v84, v2
	v_mov_b32_e32 v85, v2
	v_mov_b32_e32 v30, v2
	v_mov_b32_e32 v31, v2
	v_mov_b32_e32 v32, v2
	v_mov_b32_e32 v33, v2
	v_mov_b32_e32 v94, v2
	v_mov_b32_e32 v95, v2
	v_mov_b32_e32 v96, v2
	v_mov_b32_e32 v97, v2
	v_mov_b32_e32 v34, v2
	v_mov_b32_e32 v35, v2
	v_mov_b32_e32 v36, v2
	v_mov_b32_e32 v37, v2
	v_mov_b32_e32 v98, v2
	v_mov_b32_e32 v99, v2
	v_mov_b32_e32 v100, v2
	v_mov_b32_e32 v101, v2
	v_mov_b32_e32 v38, v2
	v_mov_b32_e32 v39, v2
	v_mov_b32_e32 v40, v2
	v_mov_b32_e32 v41, v2
	v_mov_b32_e32 v134, v2
	v_mov_b32_e32 v135, v2
	v_mov_b32_e32 v136, v2
	v_mov_b32_e32 v137, v2
	v_mov_b32_e32 v46, v2
	v_mov_b32_e32 v47, v2
	v_mov_b32_e32 v48, v2
	v_mov_b32_e32 v49, v2
	v_mov_b32_e32 v142, v2
	v_mov_b32_e32 v143, v2
	v_mov_b32_e32 v144, v2
	v_mov_b32_e32 v145, v2
	v_mov_b32_e32 v54, v2
	v_mov_b32_e32 v55, v2
	v_mov_b32_e32 v56, v2
	v_mov_b32_e32 v57, v2
	v_mov_b32_e32 v150, v2
	v_mov_b32_e32 v151, v2
	v_mov_b32_e32 v152, v2
	v_mov_b32_e32 v153, v2
	v_mov_b32_e32 v58, v2
	v_mov_b32_e32 v59, v2
	v_mov_b32_e32 v60, v2
	v_mov_b32_e32 v61, v2
	v_mov_b32_e32 v154, v2
	v_mov_b32_e32 v155, v2
	v_mov_b32_e32 v156, v2
	v_mov_b32_e32 v157, v2
	v_mov_b32_e32 v42, v2
	v_mov_b32_e32 v43, v2
	v_mov_b32_e32 v44, v2
	v_mov_b32_e32 v45, v2
	v_mov_b32_e32 v138, v2
	v_mov_b32_e32 v139, v2
	v_mov_b32_e32 v140, v2
	v_mov_b32_e32 v141, v2
	v_mov_b32_e32 v50, v2
	v_mov_b32_e32 v51, v2
	v_mov_b32_e32 v52, v2
	v_mov_b32_e32 v53, v2
	v_mov_b32_e32 v146, v2
	v_mov_b32_e32 v147, v2
	v_mov_b32_e32 v148, v2
	v_mov_b32_e32 v149, v2
	v_mov_b32_e32 v62, v2
	v_mov_b32_e32 v63, v2
	v_mov_b32_e32 v64, v2
	v_mov_b32_e32 v65, v2
	v_mov_b32_e32 v158, v2
	v_mov_b32_e32 v159, v2
	v_mov_b32_e32 v160, v2
	v_mov_b32_e32 v161, v2
	v_mov_b32_e32 v66, v2
	v_mov_b32_e32 v67, v2
	v_mov_b32_e32 v68, v2
	v_mov_b32_e32 v69, v2
	v_mov_b32_e32 v162, v2
	v_mov_b32_e32 v163, v2
	v_mov_b32_e32 v164, v2
	v_mov_b32_e32 v165, v2

; template <class Epi, bool SEG>
; __device__ __forceinline__ void gemm_phase(LAS unsigned char* lds, const Gemm g, const int G, const int cidx, const Epi& E) {
;     ...
;         const bool has_next = S.next(ui + 1, nxt);
;         const char* nA = has_next ? (const char*)g.A + (long)nxt.pm * (long)tstepA + aoff0 : cA; const char* nB = has_next ? (const char*)g.Bt + (size_t)nxt.pn * tstepB : cB;
;     ...
;         for (int a = 0; a < 2; ++a)
; #pragma unroll
;             for (int b = 0; b < 2; ++b)
; #pragma unroll
;                 for (int m = 0; m < 4; ++m)
; #pragma unroll
;                     for (int n = 0; n < 2; ++n) acc[a][b][m][n] = (f32x4){0.f, 0.f, 0.f, 0.f};
.LBB0_957:
	s_add_u32 s52, s20, 0x100
	v_mov_b32_e32 v2, 0
	s_addc_u32 s53, s21, 0
	s_mov_b32 s54, -2
	s_waitcnt lgkmcnt(0)
	v_mov_b32_e32 v3, v2
	v_mov_b32_e32 v4, v2
	v_mov_b32_e32 v5, v2
	v_mov_b32_e32 v6, v2
	v_mov_b32_e32 v7, v2
	v_mov_b32_e32 v8, v2
	v_mov_b32_e32 v9, v2
	v_mov_b32_e32 v22, v2
	v_mov_b32_e32 v23, v2
	v_mov_b32_e32 v24, v2
	v_mov_b32_e32 v25, v2
	v_mov_b32_e32 v26, v2
	v_mov_b32_e32 v27, v2
	v_mov_b32_e32 v28, v2
	v_mov_b32_e32 v29, v2
	v_mov_b32_e32 v38, v2
	v_mov_b32_e32 v39, v2
	v_mov_b32_e32 v40, v2
	v_mov_b32_e32 v41, v2
	v_mov_b32_e32 v42, v2
	v_mov_b32_e32 v43, v2
	v_mov_b32_e32 v44, v2
	v_mov_b32_e32 v45, v2
	v_mov_b32_e32 v54, v2
	v_mov_b32_e32 v55, v2
	v_mov_b32_e32 v56, v2
	v_mov_b32_e32 v57, v2
	v_mov_b32_e32 v58, v2
	v_mov_b32_e32 v59, v2
	v_mov_b32_e32 v60, v2
	v_mov_b32_e32 v61, v2
	v_mov_b32_e32 v10, v2
	v_mov_b32_e32 v11, v2
	v_mov_b32_e32 v12, v2
	v_mov_b32_e32 v13, v2
	v_mov_b32_e32 v18, v2
	v_mov_b32_e32 v19, v2
	v_mov_b32_e32 v20, v2
	v_mov_b32_e32 v21, v2
	v_mov_b32_e32 v30, v2
	v_mov_b32_e32 v31, v2
	v_mov_b32_e32 v32, v2
	v_mov_b32_e32 v33, v2
	v_mov_b32_e32 v34, v2
	v_mov_b32_e32 v35, v2
	v_mov_b32_e32 v36, v2
	v_mov_b32_e32 v37, v2
	v_mov_b32_e32 v46, v2
	v_mov_b32_e32 v47, v2
	v_mov_b32_e32 v48, v2
	v_mov_b32_e32 v49, v2
	v_mov_b32_e32 v50, v2
	v_mov_b32_e32 v51, v2
	v_mov_b32_e32 v52, v2
	v_mov_b32_e32 v53, v2
	v_mov_b32_e32 v62, v2
	v_mov_b32_e32 v63, v2
	v_mov_b32_e32 v64, v2
	v_mov_b32_e32 v65, v2
	v_mov_b32_e32 v66, v2
	v_mov_b32_e32 v67, v2
	v_mov_b32_e32 v68, v2
	v_mov_b32_e32 v69, v2
	v_mov_b32_e32 v70, v2
	v_mov_b32_e32 v71, v2
	v_mov_b32_e32 v72, v2
	v_mov_b32_e32 v73, v2
	v_mov_b32_e32 v74, v2
	v_mov_b32_e32 v75, v2
	v_mov_b32_e32 v76, v2
	v_mov_b32_e32 v77, v2
	v_mov_b32_e32 v86, v2
	v_mov_b32_e32 v87, v2
	v_mov_b32_e32 v88, v2
	v_mov_b32_e32 v89, v2
	v_mov_b32_e32 v90, v2
	v_mov_b32_e32 v91, v2
	v_mov_b32_e32 v92, v2
	v_mov_b32_e32 v93, v2
	v_mov_b32_e32 v102, v2
	v_mov_b32_e32 v103, v2
	v_mov_b32_e32 v104, v2
	v_mov_b32_e32 v105, v2
	v_mov_b32_e32 v106, v2
	v_mov_b32_e32 v107, v2
	v_mov_b32_e32 v108, v2
	v_mov_b32_e32 v109, v2
	v_mov_b32_e32 v118, v2
	v_mov_b32_e32 v119, v2
	v_mov_b32_e32 v120, v2
	v_mov_b32_e32 v121, v2
	v_mov_b32_e32 v122, v2
	v_mov_b32_e32 v123, v2
	v_mov_b32_e32 v124, v2
	v_mov_b32_e32 v125, v2
	v_mov_b32_e32 v78, v2
	v_mov_b32_e32 v79, v2
	v_mov_b32_e32 v80, v2
	v_mov_b32_e32 v81, v2
	v_mov_b32_e32 v82, v2
	v_mov_b32_e32 v83, v2
	v_mov_b32_e32 v84, v2
	v_mov_b32_e32 v85, v2
	v_mov_b32_e32 v94, v2
	v_mov_b32_e32 v95, v2
	v_mov_b32_e32 v96, v2
	v_mov_b32_e32 v97, v2
	v_mov_b32_e32 v98, v2
	v_mov_b32_e32 v99, v2
	v_mov_b32_e32 v100, v2
	v_mov_b32_e32 v101, v2
	v_mov_b32_e32 v110, v2
	v_mov_b32_e32 v111, v2
	v_mov_b32_e32 v112, v2
	v_mov_b32_e32 v113, v2
	v_mov_b32_e32 v114, v2
	v_mov_b32_e32 v115, v2
	v_mov_b32_e32 v116, v2
	v_mov_b32_e32 v117, v2
	v_mov_b32_e32 v126, v2
	v_mov_b32_e32 v127, v2
	v_mov_b32_e32 v128, v2
	v_mov_b32_e32 v129, v2
	v_mov_b32_e32 v134, v2
	v_mov_b32_e32 v135, v2
	v_mov_b32_e32 v136, v2
	v_mov_b32_e32 v137, v2

.LBB0_1156:
	v_max_f32_e32 v0, v67, v67
	v_max_f32_e32 v102, v66, v66
	v_max3_f32 v103, v77, v78, v79
	v_max_f32_e32 v0, v102, v0
	v_max3_f32 v103, v103, v80, v81
	v_max3_f32 v0, v0, v82, v68
	v_max3_f32 v103, v103, v83, v84
	v_max3_f32 v0, v0, v69, v70
	ds_read_b128 v[98:101], v217 offset:13312
	ds_read_b128 v[186:189], v217 offset:13344
	ds_read_b128 v[194:197], v217 offset:19968
	ds_read_b128 v[190:193], v217 offset:20000
	ds_read_b128 v[182:185], v217 offset:13376
	ds_read_b128 v[174:177], v217 offset:13408
	ds_read_b128 v[178:181], v217 offset:20032
	ds_read_b128 v[170:173], v217 offset:20064
	ds_read_b128 v[166:169], v217 offset:13440
	ds_read_b128 v[158:161], v217 offset:13472
	ds_read_b128 v[162:165], v217 offset:20096
	ds_read_b128 v[154:157], v217 offset:20128
	v_max3_f32 v103, v103, v85, v86
	v_max3_f32 v0, v0, v71, v72
	v_max3_f32 v103, v103, v87, v88
	v_max3_f32 v0, v0, v73, v74
	v_max3_f32 v103, v103, v89, v90
	v_max3_f32 v0, v0, v75, v76
	v_max3_f32 v103, v103, v91, v92
	v_max3_f32 v0, v0, v93, v94
	v_max3_f32 v103, v103, v95, v96
	v_max3_f32 v0, v0, v103, v97
	v_mov_b32_e32 v102, v0
	s_nop 1
	v_permlane32_swap_b32_e32 v0, v102
	v_max_f32_e32 v102, v102, v102
	v_max_f32_e32 v0, v0, v0
	v_max_f32_e32 v0, v0, v102
	v_cmp_lt_f32_e32 vcc, s33, v0
	s_cbranch_vccz .LBB0_1158
	v_max_f32_e32 v0, v0, v0
	v_max_f32_e32 v0, 0, v0
	v_exp_f32_e64 v102, -v0
	v_add_f32_e32 v199, v199, v0
	v_xor_b32_e32 v50, 0x80000000, v199
	v_pk_add_f32 v[66:67], v[66:67], v[0:1] op_sel_hi:[1,0] neg_lo:[0,1] neg_hi:[0,1]
	v_pk_add_f32 v[82:83], v[82:83], v[0:1] op_sel_hi:[1,0] neg_lo:[0,1] neg_hi:[0,1]
	v_pk_add_f32 v[68:69], v[68:69], v[0:1] op_sel_hi:[1,0] neg_lo:[0,1] neg_hi:[0,1]
	v_pk_add_f32 v[84:85], v[84:85], v[0:1] op_sel_hi:[1,0] neg_lo:[0,1] neg_hi:[0,1]
	v_pk_add_f32 v[70:71], v[70:71], v[0:1] op_sel_hi:[1,0] neg_lo:[0,1] neg_hi:[0,1]
	v_pk_add_f32 v[86:87], v[86:87], v[0:1] op_sel_hi:[1,0] neg_lo:[0,1] neg_hi:[0,1]
	v_pk_add_f32 v[72:73], v[72:73], v[0:1] op_sel_hi:[1,0] neg_lo:[0,1] neg_hi:[0,1]
	v_pk_add_f32 v[88:89], v[88:89], v[0:1] op_sel_hi:[1,0] neg_lo:[0,1] neg_hi:[0,1]
	v_pk_add_f32 v[74:75], v[74:75], v[0:1] op_sel_hi:[1,0] neg_lo:[0,1] neg_hi:[0,1]
	v_pk_add_f32 v[90:91], v[90:91], v[0:1] op_sel_hi:[1,0] neg_lo:[0,1] neg_hi:[0,1]
	v_pk_add_f32 v[76:77], v[76:77], v[0:1] op_sel_hi:[1,0] neg_lo:[0,1] neg_hi:[0,1]
	v_pk_add_f32 v[92:93], v[92:93], v[0:1] op_sel_hi:[1,0] neg_lo:[0,1] neg_hi:[0,1]
	v_pk_add_f32 v[78:79], v[78:79], v[0:1] op_sel_hi:[1,0] neg_lo:[0,1] neg_hi:[0,1]
	v_pk_add_f32 v[94:95], v[94:95], v[0:1] op_sel_hi:[1,0] neg_lo:[0,1] neg_hi:[0,1]
	v_pk_mul_f32 v[48:49], v[48:49], v[102:103] op_sel_hi:[1,0]
	v_pk_mul_f32 v[46:47], v[46:47], v[102:103] op_sel_hi:[1,0]
	v_pk_mul_f32 v[44:45], v[44:45], v[102:103] op_sel_hi:[1,0]
	v_pk_mul_f32 v[42:43], v[42:43], v[102:103] op_sel_hi:[1,0]
	v_pk_mul_f32 v[40:41], v[40:41], v[102:103] op_sel_hi:[1,0]
	v_pk_mul_f32 v[38:39], v[38:39], v[102:103] op_sel_hi:[1,0]
	v_pk_mul_f32 v[36:37], v[36:37], v[102:103] op_sel_hi:[1,0]
	v_pk_mul_f32 v[34:35], v[34:35], v[102:103] op_sel_hi:[1,0]
	v_pk_mul_f32 v[32:33], v[32:33], v[102:103] op_sel_hi:[1,0]
	v_pk_mul_f32 v[30:31], v[30:31], v[102:103] op_sel_hi:[1,0]
	v_pk_mul_f32 v[28:29], v[28:29], v[102:103] op_sel_hi:[1,0]
	v_pk_mul_f32 v[26:27], v[26:27], v[102:103] op_sel_hi:[1,0]
	v_pk_mul_f32 v[24:25], v[24:25], v[102:103] op_sel_hi:[1,0]
	v_pk_mul_f32 v[22:23], v[22:23], v[102:103] op_sel_hi:[1,0]
	v_pk_mul_f32 v[20:21], v[20:21], v[102:103] op_sel_hi:[1,0]
	v_pk_mul_f32 v[18:19], v[18:19], v[102:103] op_sel_hi:[1,0]
	v_pk_add_f32 v[80:81], v[80:81], v[0:1] op_sel_hi:[1,0] neg_lo:[0,1] neg_hi:[0,1]
	v_pk_add_f32 v[96:97], v[96:97], v[0:1] op_sel_hi:[1,0] neg_lo:[0,1] neg_hi:[0,1]
	v_mov_b32_e32 v51, v50
	v_mov_b32_e32 v52, v50
	v_mov_b32_e32 v53, v50
	v_mov_b32_e32 v54, v50
	v_mov_b32_e32 v55, v50
	v_mov_b32_e32 v56, v50
	v_mov_b32_e32 v57, v50
	v_mov_b32_e32 v58, v50
	v_mov_b32_e32 v59, v50
	v_mov_b32_e32 v60, v50
	v_mov_b32_e32 v61, v50
	v_mov_b32_e32 v62, v50
	v_mov_b32_e32 v63, v50
	v_mov_b32_e32 v64, v50
	v_mov_b32_e32 v65, v50
	v_mul_f32_e32 v198, v198, v102

.LBB0_1164:
	v_max_f32_e32 v0, v115, v115
	v_max_f32_e32 v66, v114, v114
	v_max3_f32 v67, v125, v126, v127
	v_max_f32_e32 v0, v66, v0
	v_max3_f32 v67, v67, v128, v129
	v_max3_f32 v0, v0, v98, v116
	v_max3_f32 v67, v67, v99, v100
	v_max3_f32 v0, v0, v117, v118
	ds_read_b128 v[82:85], v217
	ds_read_b128 v[186:189], v217 offset:32
	ds_read_b128 v[194:197], v217 offset:6656
	ds_read_b128 v[190:193], v217 offset:6688
	ds_read_b128 v[182:185], v217 offset:64
	ds_read_b128 v[174:177], v217 offset:96
	ds_read_b128 v[178:181], v217 offset:6720
	ds_read_b128 v[170:173], v217 offset:6752
	ds_read_b128 v[166:169], v217 offset:128
	ds_read_b128 v[158:161], v217 offset:160
	ds_read_b128 v[162:165], v217 offset:6784
	ds_read_b128 v[154:157], v217 offset:6816
	v_max3_f32 v67, v67, v101, v102
	v_max3_f32 v0, v0, v119, v120
	v_max3_f32 v67, v67, v103, v104
	v_max3_f32 v0, v0, v121, v122
	v_max3_f32 v67, v67, v105, v106
	v_max3_f32 v0, v0, v123, v124
	v_max3_f32 v67, v67, v107, v108
	v_max3_f32 v0, v0, v110, v111
	v_max3_f32 v67, v67, v109, v112
	v_max3_f32 v0, v0, v67, v113
	v_mov_b32_e32 v66, v0
	s_nop 1
	v_permlane32_swap_b32_e32 v0, v66
	v_max_f32_e32 v66, v66, v66
	v_max_f32_e32 v0, v0, v0
	v_max_f32_e32 v0, v0, v66
	v_cmp_lt_f32_e32 vcc, s33, v0
	s_cbranch_vccz .LBB0_1142
	v_max_f32_e32 v0, v0, v0
	v_max_f32_e32 v0, 0, v0
	v_exp_f32_e64 v66, -v0
	v_add_f32_e32 v199, v199, v0
	v_xor_b32_e32 v50, 0x80000000, v199
	v_pk_add_f32 v[114:115], v[114:115], v[0:1] op_sel_hi:[1,0] neg_lo:[0,1] neg_hi:[0,1]
	v_pk_add_f32 v[98:99], v[98:99], v[0:1] op_sel_hi:[1,0] neg_lo:[0,1] neg_hi:[0,1]
	v_pk_add_f32 v[116:117], v[116:117], v[0:1] op_sel_hi:[1,0] neg_lo:[0,1] neg_hi:[0,1]
	v_pk_add_f32 v[100:101], v[100:101], v[0:1] op_sel_hi:[1,0] neg_lo:[0,1] neg_hi:[0,1]
	v_pk_add_f32 v[118:119], v[118:119], v[0:1] op_sel_hi:[1,0] neg_lo:[0,1] neg_hi:[0,1]
	v_pk_add_f32 v[102:103], v[102:103], v[0:1] op_sel_hi:[1,0] neg_lo:[0,1] neg_hi:[0,1]
	v_pk_add_f32 v[120:121], v[120:121], v[0:1] op_sel_hi:[1,0] neg_lo:[0,1] neg_hi:[0,1]
	v_pk_add_f32 v[104:105], v[104:105], v[0:1] op_sel_hi:[1,0] neg_lo:[0,1] neg_hi:[0,1]
	v_pk_add_f32 v[122:123], v[122:123], v[0:1] op_sel_hi:[1,0] neg_lo:[0,1] neg_hi:[0,1]
	v_pk_add_f32 v[106:107], v[106:107], v[0:1] op_sel_hi:[1,0] neg_lo:[0,1] neg_hi:[0,1]
	v_pk_add_f32 v[124:125], v[124:125], v[0:1] op_sel_hi:[1,0] neg_lo:[0,1] neg_hi:[0,1]
	v_pk_add_f32 v[108:109], v[108:109], v[0:1] op_sel_hi:[1,0] neg_lo:[0,1] neg_hi:[0,1]
	v_pk_add_f32 v[126:127], v[126:127], v[0:1] op_sel_hi:[1,0] neg_lo:[0,1] neg_hi:[0,1]
	v_pk_add_f32 v[110:111], v[110:111], v[0:1] op_sel_hi:[1,0] neg_lo:[0,1] neg_hi:[0,1]
	v_pk_mul_f32 v[48:49], v[48:49], v[66:67] op_sel_hi:[1,0]
	v_pk_mul_f32 v[46:47], v[46:47], v[66:67] op_sel_hi:[1,0]
	v_pk_mul_f32 v[44:45], v[44:45], v[66:67] op_sel_hi:[1,0]
	v_pk_mul_f32 v[42:43], v[42:43], v[66:67] op_sel_hi:[1,0]
	v_pk_mul_f32 v[40:41], v[40:41], v[66:67] op_sel_hi:[1,0]
	v_pk_mul_f32 v[38:39], v[38:39], v[66:67] op_sel_hi:[1,0]
	v_pk_mul_f32 v[36:37], v[36:37], v[66:67] op_sel_hi:[1,0]
	v_pk_mul_f32 v[34:35], v[34:35], v[66:67] op_sel_hi:[1,0]
	v_pk_mul_f32 v[32:33], v[32:33], v[66:67] op_sel_hi:[1,0]
	v_pk_mul_f32 v[30:31], v[30:31], v[66:67] op_sel_hi:[1,0]
	v_pk_mul_f32 v[28:29], v[28:29], v[66:67] op_sel_hi:[1,0]
	v_pk_mul_f32 v[26:27], v[26:27], v[66:67] op_sel_hi:[1,0]
	v_pk_mul_f32 v[24:25], v[24:25], v[66:67] op_sel_hi:[1,0]
	v_pk_mul_f32 v[22:23], v[22:23], v[66:67] op_sel_hi:[1,0]
	v_pk_mul_f32 v[20:21], v[20:21], v[66:67] op_sel_hi:[1,0]
	v_pk_mul_f32 v[18:19], v[18:19], v[66:67] op_sel_hi:[1,0]
	v_pk_add_f32 v[128:129], v[128:129], v[0:1] op_sel_hi:[1,0] neg_lo:[0,1] neg_hi:[0,1]
	v_pk_add_f32 v[112:113], v[112:113], v[0:1] op_sel_hi:[1,0] neg_lo:[0,1] neg_hi:[0,1]
	v_mov_b32_e32 v51, v50
	v_mov_b32_e32 v52, v50
	v_mov_b32_e32 v53, v50
	v_mov_b32_e32 v54, v50
	v_mov_b32_e32 v55, v50
	v_mov_b32_e32 v56, v50
	v_mov_b32_e32 v57, v50
	v_mov_b32_e32 v58, v50
	v_mov_b32_e32 v59, v50
	v_mov_b32_e32 v60, v50
	v_mov_b32_e32 v61, v50
	v_mov_b32_e32 v62, v50
	v_mov_b32_e32 v63, v50
	v_mov_b32_e32 v64, v50
	v_mov_b32_e32 v65, v50
	v_mul_f32_e32 v198, v198, v66
	s_branch .LBB0_1142
